# GEMM phases (win, gemm_f32, ffn_up): first tile of a phase loads k-tiles 0 and 1 together (k-tile 1 lands in fragment registers, copied to staging) instead of two serial cold round trips
# speedup vs baseline: 1.0019x; 1.0019x over previous
; #define ZERO_ACC8(acc, NJ_)                             \
;   _Pragma("unroll") for (int i_ = 0; i_ < 8; ++i_)      \
;   _Pragma("unroll") for (int j_ = 0; j_ < (NJ_); ++j_) { acc[i_][j_] = (f32x4){0.f, 0.f, 0.f, 0.f}; }
; template <int MI, int NJ> ...
;     ...
;   if (!pre) G8LOADP(Ag, Bg);
;   G8STORE(0);
;   {
;     const u16* ga_ = (1 < nk) ? Ag + 64 : Ag + nAoff;
;     const u16* gb_ = (1 < nk) ? Bg + 64 : Bg + nBoff;
;     G8LOADP(ga_, gb_);
;   }
;   __syncthreads();
; __device__ __forceinline__ void phase_win(const Params& p, int part, u16* smem, volatile LAS unsigned* vb_) {
;     ...
;     f32x4 acc[8][4];
;     ZERO_ACC8(acc, 4);
;     gemm8<8, 4>(acc, G8REGS_ARGS, pre, H, 1024, W, 1024, 0, 1024, mt * 256, nt * 256, nmt * 256, nnt * 256, 0, smem, tid);
;     pre = true;
.LBB0_467:
	s_and_b32 s11, s38, 7
	s_or_b32 s10, s11, s23
	s_lshl_b32 s10, s10, 8
	v_add_u32_e32 v34, s10, v184
	v_ashrrev_i32_e32 v35, 31, v34
	v_lshlrev_b64 v[34:35], 11, v[34:35]
	v_lshl_add_u64 v[180:181], v[176:177], 0, v[34:35]
	v_add_u32_e32 v34, s20, v184
	v_ashrrev_i32_e32 v35, 31, v34
	v_lshlrev_b64 v[34:35], 11, v[34:35]
	s_xor_b64 s[12:13], s[12:13], -1
	s_andn2_b64 vcc, exec, s[12:13]
	v_lshl_add_u64 v[182:183], v[178:179], 0, v[34:35]
	v_readfirstlane_b32 s62, v180
	v_readfirstlane_b32 s63, v181
	v_readfirstlane_b32 s64, v182
	v_readfirstlane_b32 s65, v183
	s_nop 4
	s_cbranch_vccnz .LBB0_469
	global_load_dwordx4 v[10:13], v234, s[62:63]
	global_load_dwordx4 v[2:5], v235, s[62:63]
	global_load_dwordx4 v[6:9], v236, s[62:63]
	global_load_dwordx4 v[18:21], v237, s[62:63]
	global_load_dwordx4 v[14:17], v234, s[64:65]
	global_load_dwordx4 v[22:25], v235, s[64:65]
	global_load_dwordx4 v[26:29], v236, s[64:65]
	global_load_dwordx4 v[30:33], v237, s[64:65]
	global_load_dwordx4 v[212:215], v234, s[62:63] offset:128
	global_load_dwordx4 v[216:219], v235, s[62:63] offset:128
	global_load_dwordx4 v[220:223], v236, s[62:63] offset:128
	global_load_dwordx4 v[224:227], v237, s[62:63] offset:128
	global_load_dwordx4 v[166:169], v234, s[64:65] offset:128
	global_load_dwordx4 v[170:173], v235, s[64:65] offset:128
	global_load_dwordx4 v[192:195], v236, s[64:65] offset:128
	global_load_dwordx4 v[196:199], v237, s[64:65] offset:128
	s_waitcnt vmcnt(13)
	ds_write_b128 v185, v[10:13]
	ds_write_b128 v185, v[2:5] offset:8192
	ds_write_b128 v185, v[6:9] offset:16384
	s_waitcnt vmcnt(11)
	ds_write_b128 v185, v[18:21] offset:24576
	ds_write_b128 v186, v[14:17]
	s_waitcnt vmcnt(10)
	ds_write_b128 v186, v[22:25] offset:8192
	s_waitcnt vmcnt(9)
	ds_write_b128 v186, v[26:29] offset:16384
	s_waitcnt vmcnt(8)
	ds_write_b128 v186, v[30:33] offset:24576
	s_waitcnt vmcnt(0)
	v_mov_b64_e32 v[10:11], v[212:213]
	v_mov_b64_e32 v[12:13], v[214:215]
	v_mov_b64_e32 v[2:3], v[216:217]
	v_mov_b64_e32 v[4:5], v[218:219]
	v_mov_b64_e32 v[6:7], v[220:221]
	v_mov_b64_e32 v[8:9], v[222:223]
	v_mov_b64_e32 v[18:19], v[224:225]
	v_mov_b64_e32 v[20:21], v[226:227]
	v_mov_b64_e32 v[14:15], v[166:167]
	v_mov_b64_e32 v[16:17], v[168:169]
	v_mov_b64_e32 v[22:23], v[170:171]
	v_mov_b64_e32 v[24:25], v[172:173]
	v_mov_b64_e32 v[26:27], v[192:193]
	v_mov_b64_e32 v[28:29], v[194:195]
	v_mov_b64_e32 v[30:31], v[196:197]
	v_mov_b64_e32 v[32:33], v[198:199]
	s_branch .Lk1done_win
.LBB0_469:
	s_waitcnt vmcnt(5)
	ds_write_b128 v185, v[10:13]
	ds_write_b128 v185, v[2:5] offset:8192
	ds_write_b128 v185, v[6:9] offset:16384
	s_waitcnt vmcnt(3)
	ds_write_b128 v185, v[18:21] offset:24576
	ds_write_b128 v186, v[14:17]
	s_waitcnt vmcnt(2)
	ds_write_b128 v186, v[22:25] offset:8192
	s_waitcnt vmcnt(1)
	ds_write_b128 v186, v[26:29] offset:16384
	s_waitcnt vmcnt(0)
	ds_write_b128 v186, v[30:33] offset:24576
	global_load_dwordx4 v[10:13], v234, s[62:63] offset:128
	global_load_dwordx4 v[2:5], v235, s[62:63] offset:128
	global_load_dwordx4 v[6:9], v236, s[62:63] offset:128
	global_load_dwordx4 v[18:21], v237, s[62:63] offset:128
	global_load_dwordx4 v[14:17], v234, s[64:65] offset:128
	global_load_dwordx4 v[22:25], v235, s[64:65] offset:128
	global_load_dwordx4 v[26:29], v236, s[64:65] offset:128
	global_load_dwordx4 v[30:33], v237, s[64:65] offset:128

; #define ZERO_ACC8(acc, NJ_)                             \
;   _Pragma("unroll") for (int i_ = 0; i_ < 8; ++i_)      \
;   _Pragma("unroll") for (int j_ = 0; j_ < (NJ_); ++j_) { acc[i_][j_] = (f32x4){0.f, 0.f, 0.f, 0.f}; }
; template <int MI, int NJ> ...
;     ...
;   if (!pre) G8LOADP(Ag, Bg);
;   G8STORE(0);
;   {
;     const u16* ga_ = (1 < nk) ? Ag + 64 : Ag + nAoff;
;     const u16* gb_ = (1 < nk) ? Bg + 64 : Bg + nBoff;
;     G8LOADP(ga_, gb_);
;   }
;   __syncthreads();
; __device__ __forceinline__ void phase_gemm_f32(const u16* A, const u16* Bt, int K, u16* out, u16* smem,
;                                                volatile LAS unsigned* vb_) {
;     ...
;   for (int lt = vb >> 3; lt < 8 * 4; lt += step) {
;     const int nt = lt >> 3, mt = (vb & 7) * 8 + (lt & 7);
;     const int ltn = (lt + step < 8 * 4) ? lt + step : lt;
;     f32x4 acc[8][4];
;     ZERO_ACC8(acc, 4);
;     gemm8<8, 4>(acc, G8REGS_ARGS, pre, A, K, Bt, K, 0, K, mt * 256, nt * 256, ((vb & 7) * 8 + (ltn & 7)) * 256, (ltn >> 3) * 256, 0, smem, tid);
.LBB0_478:
	s_and_b32 s38, s37, 7
	s_or_b32 s23, s38, s22
	s_lshl_b32 s23, s23, 8
	s_lshl_b32 s36, s37, 5
	s_and_b32 s42, s36, 0xffffff00
	v_add_u32_e32 v0, s23, v184
	v_mad_i64_i32 v[22:23], s[40:41], v0, s10, 0
	v_add_u32_e32 v0, s42, v184
	v_lshl_add_u64 v[180:181], v[22:23], 1, v[176:177]
	v_mad_i64_i32 v[22:23], s[40:41], v0, s10, 0
	v_lshl_add_u64 v[182:183], v[22:23], 1, v[178:179]
	v_readfirstlane_b32 s62, v180
	v_readfirstlane_b32 s63, v181
	v_readfirstlane_b32 s64, v182
	v_readfirstlane_b32 s65, v183
	s_nop 4
	s_and_b64 vcc, exec, s[12:13]
	s_cbranch_vccnz .LBB0_480
	global_load_dwordx4 v[10:13], v234, s[62:63]
	global_load_dwordx4 v[2:5], v235, s[62:63]
	global_load_dwordx4 v[6:9], v236, s[62:63]
	global_load_dwordx4 v[14:17], v237, s[62:63]
	global_load_dwordx4 v[18:21], v234, s[64:65]
	global_load_dwordx4 v[42:45], v235, s[64:65]
	global_load_dwordx4 v[62:65], v236, s[64:65]
	global_load_dwordx4 v[74:77], v237, s[64:65]
	global_load_dwordx4 v[212:215], v234, s[62:63] offset:128
	global_load_dwordx4 v[216:219], v235, s[62:63] offset:128
	global_load_dwordx4 v[220:223], v236, s[62:63] offset:128
	global_load_dwordx4 v[224:227], v237, s[62:63] offset:128
	global_load_dwordx4 v[166:169], v234, s[64:65] offset:128
	global_load_dwordx4 v[170:173], v235, s[64:65] offset:128
	global_load_dwordx4 v[192:195], v236, s[64:65] offset:128
	global_load_dwordx4 v[196:199], v237, s[64:65] offset:128
	s_waitcnt vmcnt(13)
	ds_write_b128 v185, v[10:13]
	ds_write_b128 v185, v[2:5] offset:8192
	ds_write_b128 v185, v[6:9] offset:16384
	s_waitcnt vmcnt(11)
	ds_write_b128 v185, v[14:17] offset:24576
	ds_write_b128 v186, v[18:21]
	s_waitcnt vmcnt(10)
	ds_write_b128 v186, v[42:45] offset:8192
	s_waitcnt vmcnt(9)
	ds_write_b128 v186, v[62:65] offset:16384
	s_waitcnt vmcnt(8)
	ds_write_b128 v186, v[74:77] offset:24576
	s_waitcnt vmcnt(0)
	v_mov_b64_e32 v[10:11], v[212:213]
	v_mov_b64_e32 v[12:13], v[214:215]
	v_mov_b64_e32 v[2:3], v[216:217]
	v_mov_b64_e32 v[4:5], v[218:219]
	v_mov_b64_e32 v[6:7], v[220:221]
	v_mov_b64_e32 v[8:9], v[222:223]
	v_mov_b64_e32 v[14:15], v[224:225]
	v_mov_b64_e32 v[16:17], v[226:227]
	v_mov_b64_e32 v[18:19], v[166:167]
	v_mov_b64_e32 v[20:21], v[168:169]
	v_mov_b64_e32 v[42:43], v[170:171]
	v_mov_b64_e32 v[44:45], v[172:173]
	v_mov_b64_e32 v[62:63], v[192:193]
	v_mov_b64_e32 v[64:65], v[194:195]
	v_mov_b64_e32 v[74:75], v[196:197]
	v_mov_b64_e32 v[76:77], v[198:199]
	s_branch .Lk1done_gf32

; #define ZERO_ACC8(acc, NJ_)                             \
;   _Pragma("unroll") for (int i_ = 0; i_ < 8; ++i_)      \
;   _Pragma("unroll") for (int j_ = 0; j_ < (NJ_); ++j_) { acc[i_][j_] = (f32x4){0.f, 0.f, 0.f, 0.f}; }
; template <int MI, int NJ> ...
;     ...
;   __syncthreads();
;   const int sw0 = ((lane >> 4) ^ (lane & 7)) * 8;
;   const int dsw = (sw0 ^ 32) - sw0;
;   const u16* ra_ = sA + (wm * (16 * MI) + (lane & 15)) * 64 + sw0;
;   const u16* rb_ = sB + (wn * (16 * NJ) + (lane & 15)) * 64 + sw0;
;   for (int kt = 0; kt < nk; ++kt) {
;     const int buf = kt & 1;
;     {
;       G8STORE(buf ^ 1);
;       const u16* ga_ = (kt + 2 < nk) ? Ag + (kt + 2) * 64 : Ag + nAoff;
;       const u16* gb_ = (kt + 2 < nk) ? Bg + (kt + 2) * 64 : Bg + nBoff;
;       G8LOADP(ga_, gb_);
;     }
;     __builtin_amdgcn_sched_barrier(0);
;     __builtin_amdgcn_s_setprio(1);
;     const u16* a = ra_ + buf * AROWS * 64;
;     const u16* b = rb_ + buf * BROWS * 64;
; #pragma unroll
;     for (int ks = 0; ks < 2; ++ks) {
;       const u16* a_ = ks ? a + dsw : a;
;       const u16* b_ = ks ? b + dsw : b;
;       bf16x8 bfr[NJ];
; #pragma unroll
;       for (int j = 0; j < NJ; ++j) bfr[j] = *(const bf16x8*)(b_ + j * 16 * 64);
; #pragma unroll
;       for (int ih = 0; ih < MI / 4; ++ih) {
;         bf16x8 af[4];
; #pragma unroll
;         for (int i = 0; i < 4; ++i) af[i] = *(const bf16x8*)(a_ + (ih * 4 + i) * 16 * 64);
; __device__ __forceinline__ void phase_gemm_f32(const u16* A, const u16* Bt, int K, u16* out, u16* smem,
;                                                volatile LAS unsigned* vb_) {
;     ...
;   for (int lt = vb >> 3; lt < 8 * 4; lt += step) {
;     const int nt = lt >> 3, mt = (vb & 7) * 8 + (lt & 7);
;     const int ltn = (lt + step < 8 * 4) ? lt + step : lt;
;     f32x4 acc[8][4];
;     ZERO_ACC8(acc, 4);
;     gemm8<8, 4>(acc, G8REGS_ARGS, pre, A, K, Bt, K, 0, K, mt * 256, nt * 256, ((vb & 7) * 8 + (ltn & 7)) * 256, (ltn >> 3) * 256, 0, smem, tid);
.Lk1done_gf32:
	s_add_i32 s36, s37, s70
	s_cmp_gt_i32 s36, 31
	s_cselect_b64 s[40:41], -1, 0
	s_cmp_lt_i32 s36, 32
	s_cselect_b32 s12, s36, s37
	s_and_b32 s13, s12, 7
	s_lshl_b32 s12, s12, 5
	s_and_b32 s37, s12, 0xffffff00
	s_sub_i32 s12, s13, s38
	s_lshl_b32 s13, s12, 8
	s_sub_i32 s38, s37, s42
	v_mov_b32_e32 v22, 0
	s_mul_hi_i32 s12, s13, s10
	s_mul_i32 s13, s13, s10
	s_mul_hi_i32 s37, s38, s10
	s_mul_i32 s38, s38, s10
	s_movk_i32 s39, 0x80
	s_mov_b32 s43, 0
	s_mov_b32 s44, 0
	v_mov_b32_e32 v23, v22
	v_mov_b32_e32 v24, v22
	v_mov_b32_e32 v25, v22
	v_mov_b32_e32 v26, v22
	v_mov_b32_e32 v27, v22
	v_mov_b32_e32 v28, v22
	v_mov_b32_e32 v29, v22
	v_mov_b32_e32 v30, v22
	v_mov_b32_e32 v31, v22
	v_mov_b32_e32 v32, v22
	v_mov_b32_e32 v33, v22
	v_mov_b32_e32 v34, v22
	v_mov_b32_e32 v35, v22
	v_mov_b32_e32 v36, v22
	v_mov_b32_e32 v37, v22
	v_mov_b32_e32 v38, v22
	v_mov_b32_e32 v39, v22
	v_mov_b32_e32 v40, v22
	v_mov_b32_e32 v41, v22
	v_mov_b32_e32 v46, v22
	v_mov_b32_e32 v47, v22
	v_mov_b32_e32 v48, v22
	v_mov_b32_e32 v49, v22
	v_mov_b32_e32 v50, v22
	v_mov_b32_e32 v51, v22
	v_mov_b32_e32 v52, v22
	v_mov_b32_e32 v53, v22
	v_mov_b32_e32 v54, v22
	v_mov_b32_e32 v55, v22
	v_mov_b32_e32 v56, v22
	v_mov_b32_e32 v57, v22
	v_mov_b32_e32 v58, v22
	v_mov_b32_e32 v59, v22
	v_mov_b32_e32 v60, v22
	v_mov_b32_e32 v61, v22
	v_mov_b32_e32 v66, v22
	v_mov_b32_e32 v67, v22
	v_mov_b32_e32 v68, v22
	v_mov_b32_e32 v69, v22
	v_mov_b32_e32 v70, v22
	v_mov_b32_e32 v71, v22
	v_mov_b32_e32 v72, v22
	v_mov_b32_e32 v73, v22
	v_mov_b32_e32 v78, v22
	v_mov_b32_e32 v79, v22
	v_mov_b32_e32 v80, v22
	v_mov_b32_e32 v81, v22
	v_mov_b32_e32 v82, v22
	v_mov_b32_e32 v83, v22
	v_mov_b32_e32 v84, v22
	v_mov_b32_e32 v85, v22
	v_mov_b32_e32 v86, v22
	v_mov_b32_e32 v87, v22
	v_mov_b32_e32 v88, v22
	v_mov_b32_e32 v89, v22
	v_mov_b32_e32 v90, v22
	v_mov_b32_e32 v91, v22
	v_mov_b32_e32 v92, v22
	v_mov_b32_e32 v93, v22
	v_mov_b32_e32 v94, v22
	v_mov_b32_e32 v95, v22
	v_mov_b32_e32 v96, v22
	v_mov_b32_e32 v97, v22
	v_mov_b32_e32 v98, v22
	v_mov_b32_e32 v99, v22
	v_mov_b32_e32 v100, v22
	v_mov_b32_e32 v101, v22
	v_mov_b32_e32 v102, v22
	v_mov_b32_e32 v103, v22
	v_mov_b32_e32 v104, v22
	v_mov_b32_e32 v105, v22
	v_mov_b32_e32 v106, v22
	v_mov_b32_e32 v107, v22
	v_mov_b32_e32 v108, v22
	v_mov_b32_e32 v109, v22
	v_mov_b32_e32 v110, v22
	v_mov_b32_e32 v111, v22
	v_mov_b32_e32 v112, v22
	v_mov_b32_e32 v113, v22
	v_mov_b32_e32 v114, v22
	v_mov_b32_e32 v115, v22
	v_mov_b32_e32 v116, v22
	v_mov_b32_e32 v117, v22
	v_mov_b32_e32 v118, v22
	v_mov_b32_e32 v119, v22
	v_mov_b32_e32 v120, v22
	v_mov_b32_e32 v121, v22
	v_mov_b32_e32 v122, v22
	v_mov_b32_e32 v123, v22
	v_mov_b32_e32 v124, v22
	v_mov_b32_e32 v125, v22
	v_mov_b32_e32 v126, v22
	v_mov_b32_e32 v127, v22
	v_mov_b32_e32 v128, v22
	v_mov_b32_e32 v129, v22
	v_mov_b32_e32 v130, v22
	v_mov_b32_e32 v131, v22
	v_mov_b32_e32 v132, v22
	v_mov_b32_e32 v133, v22
	v_mov_b32_e32 v134, v22
	v_mov_b32_e32 v135, v22
	v_mov_b32_e32 v136, v22
	v_mov_b32_e32 v137, v22
	v_mov_b32_e32 v138, v22
	v_mov_b32_e32 v139, v22
	v_mov_b32_e32 v140, v22
	v_mov_b32_e32 v141, v22
	v_mov_b32_e32 v142, v22
	v_mov_b32_e32 v143, v22
	v_mov_b32_e32 v144, v22
	v_mov_b32_e32 v145, v22
	v_mov_b32_e32 v146, v22
	v_mov_b32_e32 v147, v22
	v_mov_b32_e32 v148, v22
	v_mov_b32_e32 v149, v22
	v_mov_b32_e32 v150, v22
	v_mov_b32_e32 v151, v22
	v_mov_b32_e32 v152, v22
	v_mov_b32_e32 v153, v22
	v_mov_b32_e32 v154, v22
	v_mov_b32_e32 v155, v22
	v_mov_b32_e32 v156, v22
	v_mov_b32_e32 v157, v22
	v_mov_b32_e32 v158, v22
	v_mov_b32_e32 v159, v22
	v_mov_b32_e32 v160, v22
	v_mov_b32_e32 v161, v22
	s_waitcnt lgkmcnt(0)
	s_barrier
	s_and_b32 s45, s43, 0x4000
	s_xor_b32 s46, s45, 0x4000
	s_lshl_b32 s46, s46, 1
	v_add_u32_e32 v228, s46, v185
	v_add_u32_e32 v229, s46, v186
	s_add_i32 s46, s44, 2
	s_cmp_lt_u32 s46, s21
	s_cselect_b32 s47, 0, s12
	s_cselect_b32 s46, s39, s13
	s_cselect_b32 s49, 0, s37
	s_cselect_b32 s48, s39, s38
	s_lshl_b64 s[46:47], s[46:47], 1
	s_lshl_b64 s[48:49], s[48:49], 1
	s_add_u32 s50, s62, s46
	s_addc_u32 s51, s63, s47
	s_add_u32 s52, s64, s48
	s_addc_u32 s53, s65, s49
	s_lshl_b32 s45, s45, 1
	v_add_u32_e32 v0, s45, v187
	v_add_u32_e32 v191, s45, v188
	ds_read_b128 v[166:169], v191
	ds_read_b128 v[162:165], v0
	ds_read_b128 v[170:173], v191 offset:2048
	ds_read_b128 v[192:195], v191 offset:4096
	ds_read_b128 v[196:199], v191 offset:6144
	ds_read_b128 v[204:207], v0 offset:2048
	ds_read_b128 v[208:211], v0 offset:4096
	ds_read_b128 v[238:241], v0 offset:6144
	v_add_u32_e32 v191, v191, v190

; #define ZERO_ACC8(acc, NJ_)                             \
;   _Pragma("unroll") for (int i_ = 0; i_ < 8; ++i_)      \
;   _Pragma("unroll") for (int j_ = 0; j_ < (NJ_); ++j_) { acc[i_][j_] = (f32x4){0.f, 0.f, 0.f, 0.f}; }
; template <int MI, int NJ> ...
;     ...
;   if (!pre) G8LOADP(Ag, Bg);
;   G8STORE(0);
;   {
;     const u16* ga_ = (1 < nk) ? Ag + 64 : Ag + nAoff;
;     const u16* gb_ = (1 < nk) ? Bg + 64 : Bg + nBoff;
;     G8LOADP(ga_, gb_);
;   }
;   __syncthreads();
; __device__ __forceinline__ void phase_ffn_up(const Params& p, const u16* Wgu, u16* smem, volatile LAS unsigned* vb_) {
;     ...
;   for (int lt = vb >> 3; lt < 8 * 20; lt += step) {
;     const int nt = lt >> 3, mt = (vb & 7) * 8 + (lt & 7);
;     const int ltn = (lt + step < 8 * 20) ? lt + step : lt;
;     f32x4 acc[8][4];
;     ZERO_ACC8(acc, 4);
;     gemm8<8, 4>(acc, G8REGS_ARGS, pre, H, 1024, Wgu, 1024, 0, 1024, mt * 256, nt * 256,
;                 ((vb & 7) * 8 + (ltn & 7)) * 256, (ltn >> 3) * 256, 0, smem, tid);
.LBB0_598:
	s_and_b32 s22, s20, 7
	s_or_b32 s10, s22, s38
	s_lshl_b32 s39, s10, 8
	s_waitcnt vmcnt(4)
	v_add_u32_e32 v34, s39, v176
	s_ashr_i32 s40, s20, 3
	v_ashrrev_i32_e32 v35, 31, v34
	s_lshl_b32 s21, s40, 8
	v_lshlrev_b64 v[34:35], 11, v[34:35]
	v_lshl_add_u64 v[170:171], v[162:163], 0, v[34:35]
	v_add_u32_e32 v34, s21, v176
	v_ashrrev_i32_e32 v35, 31, v34
	v_lshlrev_b64 v[34:35], 11, v[34:35]
	v_lshl_add_u64 v[172:173], v[164:165], 0, v[34:35]
	v_readfirstlane_b32 s62, v170
	v_readfirstlane_b32 s63, v171
	v_readfirstlane_b32 s64, v172
	v_readfirstlane_b32 s65, v173
	s_nop 3
	s_and_b64 vcc, exec, s[12:13]
	s_cbranch_vccnz .LBB0_600
	global_load_dwordx4 v[2:5], v169, s[62:63]
	global_load_dwordx4 v[6:9], v194, s[62:63]
	global_load_dwordx4 v[10:13], v195, s[62:63]
	global_load_dwordx4 v[18:21], v198, s[62:63]
	global_load_dwordx4 v[14:17], v169, s[64:65]
	global_load_dwordx4 v[22:25], v194, s[64:65]
	global_load_dwordx4 v[26:29], v195, s[64:65]
	global_load_dwordx4 v[30:33], v198, s[64:65]
	global_load_dwordx4 v[212:215], v169, s[62:63] offset:128
	global_load_dwordx4 v[216:219], v194, s[62:63] offset:128
	global_load_dwordx4 v[220:223], v195, s[62:63] offset:128
	global_load_dwordx4 v[224:227], v198, s[62:63] offset:128
	global_load_dwordx4 v[204:207], v169, s[64:65] offset:128
	global_load_dwordx4 v[208:211], v194, s[64:65] offset:128
	global_load_dwordx4 v[234:237], v195, s[64:65] offset:128
	global_load_dwordx4 v[238:241], v198, s[64:65] offset:128
	s_waitcnt vmcnt(13)
	ds_write_b128 v185, v[2:5]
	ds_write_b128 v185, v[6:9] offset:8192
	ds_write_b128 v185, v[10:13] offset:16384
	s_waitcnt vmcnt(11)
	ds_write_b128 v185, v[18:21] offset:24576
	ds_write_b128 v186, v[14:17]
	s_waitcnt vmcnt(10)
	ds_write_b128 v186, v[22:25] offset:8192
	s_waitcnt vmcnt(9)
	ds_write_b128 v186, v[26:29] offset:16384
	s_waitcnt vmcnt(8)
	ds_write_b128 v186, v[30:33] offset:24576
	s_waitcnt vmcnt(0)
	v_mov_b64_e32 v[2:3], v[212:213]
	v_mov_b64_e32 v[4:5], v[214:215]
	v_mov_b64_e32 v[6:7], v[216:217]
	v_mov_b64_e32 v[8:9], v[218:219]
	v_mov_b64_e32 v[10:11], v[220:221]
	v_mov_b64_e32 v[12:13], v[222:223]
	v_mov_b64_e32 v[18:19], v[224:225]
	v_mov_b64_e32 v[20:21], v[226:227]
	v_mov_b64_e32 v[14:15], v[204:205]
	v_mov_b64_e32 v[16:17], v[206:207]
	v_mov_b64_e32 v[22:23], v[208:209]
	v_mov_b64_e32 v[24:25], v[210:211]
	v_mov_b64_e32 v[26:27], v[234:235]
	v_mov_b64_e32 v[28:29], v[236:237]
	v_mov_b64_e32 v[30:31], v[238:239]
	v_mov_b64_e32 v[32:33], v[240:241]
	s_branch .Lk1done_ffn
.LBB0_600:
	s_waitcnt vmcnt(5)
	ds_write_b128 v185, v[2:5]
	ds_write_b128 v185, v[6:9] offset:8192
	ds_write_b128 v185, v[10:13] offset:16384
	s_waitcnt vmcnt(3)
	ds_write_b128 v185, v[18:21] offset:24576
	ds_write_b128 v186, v[14:17]
	s_waitcnt vmcnt(2)
	ds_write_b128 v186, v[22:25] offset:8192
	s_waitcnt vmcnt(1)
	ds_write_b128 v186, v[26:29] offset:16384
	s_waitcnt vmcnt(0)
	ds_write_b128 v186, v[30:33] offset:24576
	global_load_dwordx4 v[2:5], v169, s[62:63] offset:128
	global_load_dwordx4 v[6:9], v194, s[62:63] offset:128
	global_load_dwordx4 v[10:13], v195, s[62:63] offset:128
	global_load_dwordx4 v[18:21], v198, s[62:63] offset:128
	global_load_dwordx4 v[14:17], v169, s[64:65] offset:128
	global_load_dwordx4 v[22:25], v194, s[64:65] offset:128
	global_load_dwordx4 v[26:29], v195, s[64:65] offset:128
	global_load_dwordx4 v[30:33], v198, s[64:65] offset:128
; #define ZERO_ACC8(acc, NJ_)                             \
;   _Pragma("unroll") for (int i_ = 0; i_ < 8; ++i_)      \
;   _Pragma("unroll") for (int j_ = 0; j_ < (NJ_); ++j_) { acc[i_][j_] = (f32x4){0.f, 0.f, 0.f, 0.f}; }
; template <int MI, int NJ> ...
;     ...
;   __syncthreads();
;   const int sw0 = ((lane >> 4) ^ (lane & 7)) * 8;
;   const int dsw = (sw0 ^ 32) - sw0;
;   const u16* ra_ = sA + (wm * (16 * MI) + (lane & 15)) * 64 + sw0;
;   const u16* rb_ = sB + (wn * (16 * NJ) + (lane & 15)) * 64 + sw0;
;   for (int kt = 0; kt < nk; ++kt) {
;     const int buf = kt & 1;
;     {
;       G8STORE(buf ^ 1);
;       const u16* ga_ = (kt + 2 < nk) ? Ag + (kt + 2) * 64 : Ag + nAoff;
;       const u16* gb_ = (kt + 2 < nk) ? Bg + (kt + 2) * 64 : Bg + nBoff;
;       G8LOADP(ga_, gb_);
;     }
;     __builtin_amdgcn_sched_barrier(0);
;     __builtin_amdgcn_s_setprio(1);
;     const u16* a = ra_ + buf * AROWS * 64;
;     const u16* b = rb_ + buf * BROWS * 64;
; #pragma unroll
;     for (int ks = 0; ks < 2; ++ks) {
;       const u16* a_ = ks ? a + dsw : a;
;       const u16* b_ = ks ? b + dsw : b;
;       bf16x8 bfr[NJ];
; #pragma unroll
;       for (int j = 0; j < NJ; ++j) bfr[j] = *(const bf16x8*)(b_ + j * 16 * 64);
; #pragma unroll
;       for (int ih = 0; ih < MI / 4; ++ih) {
;         bf16x8 af[4];
; #pragma unroll
;         for (int i = 0; i < 4; ++i) af[i] = *(const bf16x8*)(a_ + (ih * 4 + i) * 16 * 64);
; __device__ __forceinline__ void phase_ffn_up(const Params& p, const u16* Wgu, u16* smem, volatile LAS unsigned* vb_) {
;     ...
;   for (int lt = vb >> 3; lt < 8 * 20; lt += step) {
;     const int nt = lt >> 3, mt = (vb & 7) * 8 + (lt & 7);
;     const int ltn = (lt + step < 8 * 20) ? lt + step : lt;
;     f32x4 acc[8][4];
;     ZERO_ACC8(acc, 4);
;     gemm8<8, 4>(acc, G8REGS_ARGS, pre, H, 1024, Wgu, 1024, 0, 1024, mt * 256, nt * 256,
;                 ((vb & 7) * 8 + (ltn & 7)) * 256, (ltn >> 3) * 256, 0, smem, tid);
.Lk1done_ffn:
	s_add_i32 s41, s20, s70
	s_cmpk_gt_i32 s41, 0x9f
	s_cselect_b64 s[10:11], -1, 0
	s_cmpk_lt_i32 s41, 0xa0
	s_cselect_b32 s12, s41, s20
	s_and_b32 s13, s12, 7
	s_lshl_b32 s12, s12, 5
	s_and_b32 s20, s12, 0xffffff00
	s_sub_i32 s12, s13, s22
	s_lshl_b32 s12, s12, 8
	s_sub_i32 s20, s20, s21
	s_ashr_i32 s13, s12, 31
	s_ashr_i32 s21, s20, 31
	v_mov_b32_e32 v34, 0
	s_lshl_b64 s[12:13], s[12:13], 10
	s_lshl_b64 s[20:21], s[20:21], 10
	s_mov_b32 s42, 0
	s_mov_b64 s[22:23], 0x80
	s_mov_b32 s43, 0
	v_mov_b32_e32 v35, v34
	v_mov_b32_e32 v36, v34
	v_mov_b32_e32 v37, v34
	v_mov_b32_e32 v38, v34
	v_mov_b32_e32 v39, v34
	v_mov_b32_e32 v40, v34
	v_mov_b32_e32 v41, v34
	v_mov_b32_e32 v42, v34
	v_mov_b32_e32 v43, v34
	v_mov_b32_e32 v44, v34
	v_mov_b32_e32 v45, v34
	v_mov_b32_e32 v46, v34
	v_mov_b32_e32 v47, v34
	v_mov_b32_e32 v48, v34
	v_mov_b32_e32 v49, v34
	v_mov_b32_e32 v50, v34
	v_mov_b32_e32 v51, v34
	v_mov_b32_e32 v52, v34
	v_mov_b32_e32 v53, v34
	v_mov_b32_e32 v54, v34
	v_mov_b32_e32 v55, v34
	v_mov_b32_e32 v56, v34
	v_mov_b32_e32 v57, v34
	v_mov_b32_e32 v58, v34
	v_mov_b32_e32 v59, v34
	v_mov_b32_e32 v60, v34
	v_mov_b32_e32 v61, v34
	v_mov_b32_e32 v62, v34
	v_mov_b32_e32 v63, v34
	v_mov_b32_e32 v64, v34
	v_mov_b32_e32 v65, v34
	v_mov_b32_e32 v66, v34
	v_mov_b32_e32 v67, v34
	v_mov_b32_e32 v68, v34
	v_mov_b32_e32 v69, v34
	v_mov_b32_e32 v70, v34
	v_mov_b32_e32 v71, v34
	v_mov_b32_e32 v72, v34
	v_mov_b32_e32 v73, v34
	v_mov_b32_e32 v74, v34
	v_mov_b32_e32 v75, v34
	v_mov_b32_e32 v76, v34
	v_mov_b32_e32 v77, v34
	v_mov_b32_e32 v78, v34
	v_mov_b32_e32 v79, v34
	v_mov_b32_e32 v80, v34
	v_mov_b32_e32 v81, v34
	v_mov_b32_e32 v82, v34
	v_mov_b32_e32 v83, v34
	v_mov_b32_e32 v84, v34
	v_mov_b32_e32 v85, v34
	v_mov_b32_e32 v86, v34
	v_mov_b32_e32 v87, v34
	v_mov_b32_e32 v88, v34
	v_mov_b32_e32 v89, v34
	v_mov_b32_e32 v90, v34
	v_mov_b32_e32 v91, v34
	v_mov_b32_e32 v92, v34
	v_mov_b32_e32 v93, v34
	v_mov_b32_e32 v94, v34
	v_mov_b32_e32 v95, v34
	v_mov_b32_e32 v96, v34
	v_mov_b32_e32 v97, v34
	v_mov_b32_e32 v98, v34
	v_mov_b32_e32 v99, v34
	v_mov_b32_e32 v100, v34
	v_mov_b32_e32 v101, v34
	v_mov_b32_e32 v102, v34
	v_mov_b32_e32 v103, v34
	v_mov_b32_e32 v104, v34
	v_mov_b32_e32 v105, v34
	v_mov_b32_e32 v106, v34
	v_mov_b32_e32 v107, v34
	v_mov_b32_e32 v108, v34
	v_mov_b32_e32 v109, v34
	v_mov_b32_e32 v110, v34
	v_mov_b32_e32 v111, v34
	v_mov_b32_e32 v112, v34
	v_mov_b32_e32 v113, v34
	v_mov_b32_e32 v114, v34
	v_mov_b32_e32 v115, v34
	v_mov_b32_e32 v116, v34
	v_mov_b32_e32 v117, v34
	v_mov_b32_e32 v118, v34
	v_mov_b32_e32 v119, v34
	v_mov_b32_e32 v120, v34
	v_mov_b32_e32 v121, v34
	v_mov_b32_e32 v122, v34
	v_mov_b32_e32 v123, v34
	v_mov_b32_e32 v124, v34
	v_mov_b32_e32 v125, v34
	v_mov_b32_e32 v126, v34
	v_mov_b32_e32 v127, v34
	v_mov_b32_e32 v128, v34
	v_mov_b32_e32 v129, v34
	v_mov_b32_e32 v130, v34
	v_mov_b32_e32 v131, v34
	v_mov_b32_e32 v132, v34
	v_mov_b32_e32 v133, v34
	v_mov_b32_e32 v134, v34
	v_mov_b32_e32 v135, v34
	v_mov_b32_e32 v136, v34
	v_mov_b32_e32 v137, v34
	v_mov_b32_e32 v138, v34
	v_mov_b32_e32 v139, v34
	v_mov_b32_e32 v140, v34
	v_mov_b32_e32 v141, v34
	v_mov_b32_e32 v142, v34
	v_mov_b32_e32 v143, v34
	v_mov_b32_e32 v144, v34
	v_mov_b32_e32 v145, v34
	v_mov_b32_e32 v146, v34
	v_mov_b32_e32 v147, v34
	v_mov_b32_e32 v148, v34
	v_mov_b32_e32 v149, v34
	v_mov_b32_e32 v150, v34
	v_mov_b32_e32 v151, v34
	v_mov_b32_e32 v152, v34
	v_mov_b32_e32 v153, v34
	v_mov_b32_e32 v154, v34
	v_mov_b32_e32 v155, v34
	v_mov_b32_e32 v156, v34
	v_mov_b32_e32 v157, v34
	v_mov_b32_e32 v158, v34
	v_mov_b32_e32 v159, v34
	v_mov_b32_e32 v160, v34
	v_mov_b32_e32 v161, v34
	s_waitcnt lgkmcnt(0)
	s_barrier
	s_and_b32 s48, s42, 0x4000
	s_xor_b32 s44, s48, 0x4000
	s_lshl_b32 s44, s44, 1
	v_add_u32_e32 v199, s44, v185
	v_add_u32_e32 v200, s44, v186
	s_cmp_lt_u32 s43, 14
	s_cselect_b32 s45, s23, s13
	s_cselect_b32 s44, s22, s12
	s_cselect_b32 s47, s23, s21
	s_cselect_b32 s46, s22, s20
	s_lshl_b64 s[44:45], s[44:45], 1
	s_lshl_b64 s[46:47], s[46:47], 1
	s_add_u32 s50, s62, s44
	s_addc_u32 s51, s63, s45
	s_add_u32 s52, s64, s46
	s_addc_u32 s53, s65, s47
	s_lshl_b32 s44, s48, 1
	v_add_u32_e32 v228, s44, v187
	v_add_u32_e32 v229, s44, v188
	ds_read_b128 v[212:215], v229
	ds_read_b128 v[208:211], v228
	ds_read_b128 v[216:219], v229 offset:2048
	ds_read_b128 v[220:223], v229 offset:4096
	ds_read_b128 v[224:227], v229 offset:6144
	ds_read_b128 v[234:237], v228 offset:2048
	ds_read_b128 v[238:241], v228 offset:4096
	ds_read_b128 v[204:207], v228 offset:6144
	v_add_u32_e32 v229, v229, v196
